# kernel entry: the four 64-byte kernel-argument scalar loads issued together and waited once (were four load-wait round trips)
# baseline (speedup 1.0000x reference)
.LBB0_12:
	s_load_dwordx16 s[20:35], s[0:1], 0x0
	s_load_dwordx16 s[40:55], s[0:1], 0x40
	s_load_dwordx16 s[56:71], s[0:1], 0x80
	s_load_dwordx16 s[4:19], s[0:1], 0xc0
	v_cmp_eq_u32_e64 s[2:3], 0, v187
	s_waitcnt lgkmcnt(0)
	v_writelane_b32 v247, s20, 1
	s_nop 1
	v_writelane_b32 v247, s21, 2
	v_writelane_b32 v247, s22, 3
	v_writelane_b32 v247, s23, 4
	v_writelane_b32 v247, s24, 5
	v_writelane_b32 v247, s25, 6
	v_writelane_b32 v247, s26, 7
	v_writelane_b32 v247, s27, 8
	v_writelane_b32 v247, s28, 9
	v_writelane_b32 v247, s29, 10
	v_writelane_b32 v247, s30, 11
	v_writelane_b32 v247, s31, 12
	v_writelane_b32 v247, s32, 13
	v_writelane_b32 v247, s33, 14
	v_writelane_b32 v247, s34, 15
	v_writelane_b32 v247, s35, 16
	v_writelane_b32 v247, s40, 17
	s_nop 1
	v_writelane_b32 v247, s41, 18
	v_writelane_b32 v247, s42, 19
	v_writelane_b32 v247, s43, 20
	v_writelane_b32 v247, s44, 21
	v_writelane_b32 v247, s45, 22
	v_writelane_b32 v247, s46, 23
	v_writelane_b32 v247, s47, 24
	v_writelane_b32 v247, s48, 25
	v_writelane_b32 v247, s49, 26
	v_writelane_b32 v247, s50, 27
	v_writelane_b32 v247, s51, 28
	v_writelane_b32 v247, s52, 29
	v_writelane_b32 v247, s53, 30
	v_writelane_b32 v247, s54, 31
	v_writelane_b32 v247, s55, 32
	v_writelane_b32 v247, s56, 33
	s_nop 1
	v_writelane_b32 v247, s57, 34
	v_writelane_b32 v247, s58, 35
	v_writelane_b32 v247, s59, 36
	v_writelane_b32 v247, s60, 37
	v_writelane_b32 v247, s61, 38
	v_writelane_b32 v247, s62, 39
	v_writelane_b32 v247, s63, 40
	v_writelane_b32 v247, s64, 41
	v_writelane_b32 v247, s65, 42
	v_writelane_b32 v247, s66, 43
	v_writelane_b32 v247, s67, 44
	v_writelane_b32 v247, s68, 45
	v_writelane_b32 v247, s69, 46
	v_writelane_b32 v247, s70, 47
	v_writelane_b32 v247, s71, 48
	v_writelane_b32 v247, s4, 49
	s_nop 1
	v_writelane_b32 v247, s5, 50
	v_writelane_b32 v247, s6, 51
	v_writelane_b32 v247, s7, 52
	v_writelane_b32 v247, s8, 53
	v_writelane_b32 v247, s9, 54
	v_writelane_b32 v247, s10, 55
	v_writelane_b32 v247, s11, 56
	v_writelane_b32 v247, s12, 57
	v_writelane_b32 v247, s13, 58
	v_writelane_b32 v247, s14, 59
	v_writelane_b32 v247, s15, 60
	v_writelane_b32 v247, s16, 61
	v_writelane_b32 v247, s17, 62
	v_writelane_b32 v247, s18, 63
	v_writelane_b32 v246, s19, 0
	s_load_dwordx16 s[16:31], s[0:1], 0x100
	s_getreg_b32 s0, hwreg(HW_REG_XCC_ID, 0, 4)
	s_and_b32 s33, s0, 15
	v_cmp_ne_u32_e64 s[4:5], 0, v187
	s_mov_b64 s[0:1], exec
	v_writelane_b32 v246, s2, 1
	s_nop 1
	v_writelane_b32 v246, s3, 2
	s_and_b64 s[2:3], s[0:1], s[2:3]
	s_mov_b64 exec, s[2:3]
	s_cbranch_execz .LBB0_15
	s_mov_b64 s[2:3], exec
	v_mbcnt_lo_u32_b32 v0, s2, 0
	v_mbcnt_hi_u32_b32 v0, s3, v0
	v_cmp_eq_u32_e32 vcc, 0, v0
	s_and_b64 s[6:7], exec, vcc
	s_mov_b64 exec, s[6:7]
	s_cbranch_execz .LBB0_15
	s_lshl_b32 s6, s33, 8
	s_bcnt1_i32_b64 s2, s[2:3]
	v_mov_b32_e32 v0, s6
	v_mov_b32_e32 v1, s2
	global_atomic_add v0, v1, s[94:95] offset:1024
